# EpiRes2 (P4,P7,P9): second-half residual loads issued with the first half instead of behind its stores
# baseline (speedup 1.0000x reference)
;     __device__ __forceinline__ void operator()(const f32x4 (&acc)[2][2][4][2], const Unit& u, int wr, int wc, int fr, int fq) const {
;     ...
;         for (int ai = 0; ai < 2; ++ai) {
;             u32x4 bw[4][2]; f32x4 bf[4][2][2];
; #pragma unroll
;             for (int m = 0; m < 4; ++m)
; #pragma unroll
;                 for (int bj = 0; bj < 2; ++bj) { const size_t off = (size_t)(row0 + ai * HALF + m * 16) * 1024 + col0 + bj * HALF;
;                     if (BASE_BF16) bw[m][bj] = *(const u32x4*)((const bf16_t*)base + off);
;                     else { bf[m][bj][0] = *(const f32x4*)((const float*)base + off); bf[m][bj][1] = *(const f32x4*)((const float*)base + off + 4); } }
; #pragma unroll
;             for (int m = 0; m < 4; ++m) {
;                 const int row = row0 + ai * HALF + m * 16; const size_t off = (size_t)row * 1024 + col0;
;                 float ss = 0.f;
; #pragma unroll
;                 for (int bj = 0; bj < 2; ++bj) {
;                     f32x4 b0, b1;
;                     if (BASE_BF16) { const u32x4 w = bw[m][bj];
;                         b0 = (f32x4){__builtin_bit_cast(float, w.x << 16), __builtin_bit_cast(float, w.x & 0xffff0000u), __builtin_bit_cast(float, w.y << 16), __builtin_bit_cast(float, w.y & 0xffff0000u)};
;                         b1 = (f32x4){__builtin_bit_cast(float, w.z << 16), __builtin_bit_cast(float, w.z & 0xffff0000u), __builtin_bit_cast(float, w.w << 16), __builtin_bit_cast(float, w.w & 0xffff0000u)}; }
;                     else { b0 = bf[m][bj][0]; b1 = bf[m][bj][1]; }
;                     const f32x4 v0 = acc[ai][bj][m][0] + b0, v1 = acc[ai][bj][m][1] + b1;
;                     ss += (v0[0] * v0[0] + v0[1] * v0[1]) + (v0[2] * v0[2] + v0[3] * v0[3]) + (v1[0] * v1[0] + v1[1] * v1[1]) + (v1[2] * v1[2] + v1[3] * v1[3]);
;                     if (OUT_BF16) { u32x4 w; w.x = cvt_pk_bf16(v0[0], v0[1]); w.y = cvt_pk_bf16(v0[2], v0[3]); w.z = cvt_pk_bf16(v1[0], v1[1]); w.w = cvt_pk_bf16(v1[2], v1[3]);
;                         *(u32x4*)((bf16_t*)out + off + bj * HALF) = w; }
;                     else { *(f32x4*)((float*)out + off + bj * HALF) = v0; *(f32x4*)((float*)out + off + bj * HALF + 4) = v1; }
;                 }
;                 ss += __shfl_xor(ss, 16); ss += __shfl_xor(ss, 32);
;                 if (fq == 0) sspart[(size_t)row * 16 + u.pn * 4 + wc] = ss;
.LBB0_919:
	v_lshl_or_b32 v168, s8, 8, v190
	v_lshl_add_u32 v172, s30, 8, v188
	v_ashrrev_i32_e32 v169, 31, v168
	v_lshlrev_b64 v[202:203], 1, v[168:169]
	v_ashrrev_i32_e32 v173, 31, v172
	v_lshl_add_u64 v[170:171], s[12:13], 0, v[202:203]
	v_lshlrev_b64 v[204:205], 11, v[172:173]
	v_lshl_add_u64 v[128:129], v[170:171], 0, v[204:205]
	global_load_dwordx4 v[194:197], v[128:129], off
	global_load_dwordx4 v[198:201], v[128:129], off offset:256
	v_or_b32_e32 v182, 16, v172
	v_or_b32_e32 v178, 32, v172
	v_or_b32_e32 v174, 48, v172
	v_ashrrev_i32_e32 v183, 31, v182
	v_ashrrev_i32_e32 v179, 31, v178
	v_ashrrev_i32_e32 v175, 31, v174
	v_lshlrev_b64 v[184:185], 11, v[182:183]
	v_lshlrev_b64 v[180:181], 11, v[178:179]
	v_lshlrev_b64 v[176:177], 11, v[174:175]
	v_lshl_add_u64 v[128:129], v[170:171], 0, v[184:185]
	v_lshl_add_u64 v[130:131], v[170:171], 0, v[180:181]
	v_lshl_add_u64 v[206:207], v[170:171], 0, v[176:177]
	global_load_dwordx4 v[148:151], v[128:129], off
	global_load_dwordx4 v[144:147], v[128:129], off offset:256
	global_load_dwordx4 v[140:143], v[130:131], off
	global_load_dwordx4 v[136:139], v[130:131], off offset:256
	global_load_dwordx4 v[132:135], v[206:207], off
	s_nop 0
	global_load_dwordx4 v[128:131], v[206:207], off offset:256
	v_add_u32_e32 v248, 0x80, v172
	v_ashrrev_i32_e32 v249, 31, v248
	v_lshlrev_b64 v[248:249], 11, v[248:249]
	v_lshl_add_u64 v[248:249], v[170:171], 0, v[248:249]
	global_load_dwordx4 v[216:219], v[248:249], off
	global_load_dwordx4 v[220:223], v[248:249], off offset:256
	v_add_u32_e32 v248, 0x90, v172
	v_ashrrev_i32_e32 v249, 31, v248
	v_lshlrev_b64 v[248:249], 11, v[248:249]
	v_lshl_add_u64 v[248:249], v[170:171], 0, v[248:249]
	global_load_dwordx4 v[224:227], v[248:249], off
	global_load_dwordx4 v[228:231], v[248:249], off offset:256
	v_add_u32_e32 v248, 0xa0, v172
	v_ashrrev_i32_e32 v249, 31, v248
	v_lshlrev_b64 v[248:249], 11, v[248:249]
	v_lshl_add_u64 v[248:249], v[170:171], 0, v[248:249]
	global_load_dwordx4 v[232:235], v[248:249], off
	global_load_dwordx4 v[236:239], v[248:249], off offset:256
	v_add_u32_e32 v248, 0xb0, v172
	v_ashrrev_i32_e32 v249, 31, v248
	v_lshlrev_b64 v[248:249], 11, v[248:249]
	v_lshl_add_u64 v[248:249], v[170:171], 0, v[248:249]
	global_load_dwordx4 v[240:243], v[248:249], off
	global_load_dwordx4 v[244:247], v[248:249], off offset:256
	s_lshl_b32 s30, s8, 2
	s_ashr_i32 s31, s30, 31
	s_waitcnt vmcnt(8)
	v_lshlrev_b32_e32 v206, 16, v194
	v_and_b32_e32 v207, 0xffff0000, v194
	v_lshlrev_b32_e32 v194, 16, v195
	v_and_b32_e32 v195, 0xffff0000, v195
	v_lshlrev_b32_e32 v208, 16, v196
	v_and_b32_e32 v209, 0xffff0000, v196
	v_lshlrev_b32_e32 v196, 16, v197
	v_and_b32_e32 v197, 0xffff0000, v197
	v_lshlrev_b32_e32 v210, 16, v198
	v_and_b32_e32 v211, 0xffff0000, v198
	v_lshlrev_b32_e32 v198, 16, v199
	v_and_b32_e32 v199, 0xffff0000, v199
	v_lshlrev_b32_e32 v214, 16, v200
	v_and_b32_e32 v215, 0xffff0000, v200
	v_lshlrev_b32_e32 v200, 16, v201
	v_and_b32_e32 v201, 0xffff0000, v201
	v_pk_add_f32 v[126:127], v[126:127], v[194:195]
	v_pk_add_f32 v[124:125], v[124:125], v[206:207]
	v_pk_add_f32 v[122:123], v[122:123], v[196:197]
	v_pk_add_f32 v[120:121], v[120:121], v[208:209]
	v_pk_add_f32 v[118:119], v[118:119], v[198:199]
	v_pk_add_f32 v[116:117], v[116:117], v[210:211]
	v_pk_add_f32 v[194:195], v[114:115], v[200:201]
	v_pk_add_f32 v[196:197], v[112:113], v[214:215]
	v_mul_f32_e32 v198, v125, v125
	v_mul_f32_e32 v199, v127, v127
	v_mul_f32_e32 v200, v121, v121
	v_mul_f32_e32 v201, v123, v123
	v_cvt_pk_bf16_f32 v112, v124, v125
	v_cvt_pk_bf16_f32 v113, v126, v127
	v_cvt_pk_bf16_f32 v114, v120, v121
	v_cvt_pk_bf16_f32 v115, v122, v123
	v_mul_f32_e32 v121, v117, v117
	v_mul_f32_e32 v123, v119, v119
	v_mul_f32_e32 v125, v197, v197
	v_fmac_f32_e32 v198, v124, v124
	v_fmac_f32_e32 v199, v126, v126
	v_fmac_f32_e32 v121, v116, v116
	v_fmac_f32_e32 v123, v118, v118
	v_mul_f32_e32 v127, v195, v195
	v_fmac_f32_e32 v200, v120, v120
	v_fmac_f32_e32 v125, v196, v196
	v_add_f32_e32 v120, v198, v199
	v_add_f32_e32 v121, v121, v123
	v_fmac_f32_e32 v201, v122, v122
	v_fmac_f32_e32 v127, v194, v194
	v_add_f32_e32 v120, v200, v120
	v_add_f32_e32 v121, v125, v121
	v_add_f32_e32 v120, v201, v120
	v_add_f32_e32 v121, v127, v121
	v_add_f32_e32 v122, v120, v121
	ds_bpermute_b32 v123, v186, v122
	v_lshl_add_u64 v[120:121], s[12:13], 0, v[204:205]
	v_lshl_add_u64 v[120:121], v[120:121], 0, v[202:203]
	global_store_dwordx4 v[120:121], v[112:115], off
	s_waitcnt lgkmcnt(0)
	s_nop 0
	v_add_f32_e32 v112, v122, v123
	ds_bpermute_b32 v113, v187, v112
	v_cvt_pk_bf16_f32 v114, v116, v117
	v_cvt_pk_bf16_f32 v115, v118, v119
	v_cvt_pk_bf16_f32 v116, v196, v197
	v_cvt_pk_bf16_f32 v117, v194, v195
	global_store_dwordx4 v[120:121], v[114:117], off offset:256
	s_and_saveexec_b64 s[34:35], s[4:5]
	s_cbranch_execz .LBB0_921
	v_lshlrev_b64 v[114:115], 6, v[172:173]
	v_lshl_add_u64 v[114:115], s[14:15], 0, v[114:115]
	v_lshl_add_u64 v[114:115], s[30:31], 2, v[114:115]
	s_lshl_b32 s8, s46, 2
	v_lshl_add_u64 v[114:115], v[114:115], 0, s[8:9]
	s_waitcnt lgkmcnt(0)
	v_add_f32_e32 v112, v112, v113
	global_store_dword v[114:115], v112, off

;     __device__ __forceinline__ void operator()(const f32x4 (&acc)[2][2][4][2], const Unit& u, int wr, int wc, int fr, int fq) const {
;     ...
;         for (int ai = 0; ai < 2; ++ai) {
;             u32x4 bw[4][2]; f32x4 bf[4][2][2];
; #pragma unroll
;             for (int m = 0; m < 4; ++m)
; #pragma unroll
;                 for (int bj = 0; bj < 2; ++bj) { const size_t off = (size_t)(row0 + ai * HALF + m * 16) * 1024 + col0 + bj * HALF;
;                     if (BASE_BF16) bw[m][bj] = *(const u32x4*)((const bf16_t*)base + off);
;                     else { bf[m][bj][0] = *(const f32x4*)((const float*)base + off); bf[m][bj][1] = *(const f32x4*)((const float*)base + off + 4); } }
; #pragma unroll
;             for (int m = 0; m < 4; ++m) {
;                 const int row = row0 + ai * HALF + m * 16; const size_t off = (size_t)row * 1024 + col0;
;                 float ss = 0.f;
; #pragma unroll
;                 for (int bj = 0; bj < 2; ++bj) {
;                     f32x4 b0, b1;
;                     if (BASE_BF16) { const u32x4 w = bw[m][bj];
;                         b0 = (f32x4){__builtin_bit_cast(float, w.x << 16), __builtin_bit_cast(float, w.x & 0xffff0000u), __builtin_bit_cast(float, w.y << 16), __builtin_bit_cast(float, w.y & 0xffff0000u)};
;                         b1 = (f32x4){__builtin_bit_cast(float, w.z << 16), __builtin_bit_cast(float, w.z & 0xffff0000u), __builtin_bit_cast(float, w.w << 16), __builtin_bit_cast(float, w.w & 0xffff0000u)}; }
;                     else { b0 = bf[m][bj][0]; b1 = bf[m][bj][1]; }
;                     const f32x4 v0 = acc[ai][bj][m][0] + b0, v1 = acc[ai][bj][m][1] + b1;
;                     ss += (v0[0] * v0[0] + v0[1] * v0[1]) + (v0[2] * v0[2] + v0[3] * v0[3]) + (v1[0] * v1[0] + v1[1] * v1[1]) + (v1[2] * v1[2] + v1[3] * v1[3]);
;                     if (OUT_BF16) { u32x4 w; w.x = cvt_pk_bf16(v0[0], v0[1]); w.y = cvt_pk_bf16(v0[2], v0[3]); w.z = cvt_pk_bf16(v1[0], v1[1]); w.w = cvt_pk_bf16(v1[2], v1[3]);
;                         *(u32x4*)((bf16_t*)out + off + bj * HALF) = w; }
;                     else { *(f32x4*)((float*)out + off + bj * HALF) = v0; *(f32x4*)((float*)out + off + bj * HALF + 4) = v1; }
;                 }
;                 ss += __shfl_xor(ss, 16); ss += __shfl_xor(ss, 32);
;                 if (fq == 0) sspart[(size_t)row * 16 + u.pn * 4 + wc] = ss;
.LBB0_927:
	s_or_b64 exec, exec, s[34:35]
	v_add_u32_e32 v100, 0x80, v172
	v_ashrrev_i32_e32 v101, 31, v100
	v_lshlrev_b64 v[110:111], 11, v[100:101]
	s_waitcnt lgkmcnt(0)
	v_lshl_add_u64 v[64:65], v[170:171], 0, v[110:111]
	v_add_u32_e32 v96, 0x90, v172
	v_add_u32_e32 v92, 0xa0, v172
	v_add_u32_e32 v88, 0xb0, v172
	v_ashrrev_i32_e32 v97, 31, v96
	v_ashrrev_i32_e32 v93, 31, v92
	v_ashrrev_i32_e32 v89, 31, v88
	v_lshlrev_b64 v[98:99], 11, v[96:97]
	v_lshlrev_b64 v[94:95], 11, v[92:93]
	v_lshlrev_b64 v[90:91], 11, v[88:89]
	v_lshl_add_u64 v[64:65], v[170:171], 0, v[98:99]
	v_lshl_add_u64 v[66:67], v[170:171], 0, v[94:95]
	v_lshl_add_u64 v[112:113], v[170:171], 0, v[90:91]
	s_nop 0
	s_waitcnt vmcnt(8)
	v_mov_b32_e32 v102, v216
	v_mov_b32_e32 v103, v217
	v_mov_b32_e32 v104, v218
	v_mov_b32_e32 v105, v219
	v_mov_b32_e32 v106, v220
	v_mov_b32_e32 v107, v221
	v_mov_b32_e32 v108, v222
	v_mov_b32_e32 v109, v223
	v_mov_b32_e32 v84, v224
	v_mov_b32_e32 v85, v225
	v_mov_b32_e32 v86, v226
	v_mov_b32_e32 v87, v227
	v_mov_b32_e32 v80, v228
	v_mov_b32_e32 v81, v229
	v_mov_b32_e32 v82, v230
	v_mov_b32_e32 v83, v231
	v_mov_b32_e32 v76, v232
	v_mov_b32_e32 v77, v233
	v_mov_b32_e32 v78, v234
	v_mov_b32_e32 v79, v235
	v_mov_b32_e32 v72, v236
	v_mov_b32_e32 v73, v237
	v_mov_b32_e32 v74, v238
	v_mov_b32_e32 v75, v239
	v_mov_b32_e32 v68, v240
	v_mov_b32_e32 v69, v241
	v_mov_b32_e32 v70, v242
	v_mov_b32_e32 v71, v243
	v_mov_b32_e32 v64, v244
	v_mov_b32_e32 v65, v245
	v_mov_b32_e32 v66, v246
	v_mov_b32_e32 v67, v247
	v_lshlrev_b32_e32 v112, 16, v102
	v_and_b32_e32 v113, 0xffff0000, v102
	v_lshlrev_b32_e32 v102, 16, v103
	v_and_b32_e32 v103, 0xffff0000, v103
	v_lshlrev_b32_e32 v114, 16, v104
	v_and_b32_e32 v115, 0xffff0000, v104
	v_lshlrev_b32_e32 v104, 16, v105
	v_and_b32_e32 v105, 0xffff0000, v105
	v_lshlrev_b32_e32 v116, 16, v106
	v_and_b32_e32 v117, 0xffff0000, v106
	v_lshlrev_b32_e32 v106, 16, v107
	v_and_b32_e32 v107, 0xffff0000, v107
	v_lshlrev_b32_e32 v118, 16, v108
	v_and_b32_e32 v119, 0xffff0000, v108
	v_lshlrev_b32_e32 v108, 16, v109
	v_and_b32_e32 v109, 0xffff0000, v109
	v_pk_add_f32 v[62:63], v[62:63], v[102:103]
	v_pk_add_f32 v[60:61], v[60:61], v[112:113]
	v_pk_add_f32 v[58:59], v[58:59], v[104:105]
	v_pk_add_f32 v[56:57], v[56:57], v[114:115]
	v_pk_add_f32 v[54:55], v[54:55], v[106:107]
	v_pk_add_f32 v[52:53], v[52:53], v[116:117]
	v_pk_add_f32 v[102:103], v[50:51], v[108:109]
	v_pk_add_f32 v[104:105], v[48:49], v[118:119]
	v_mul_f32_e32 v106, v61, v61
	v_mul_f32_e32 v107, v63, v63
	v_mul_f32_e32 v108, v57, v57
	v_mul_f32_e32 v109, v59, v59
	v_cvt_pk_bf16_f32 v48, v60, v61
	v_cvt_pk_bf16_f32 v49, v62, v63
	v_cvt_pk_bf16_f32 v50, v56, v57
	v_cvt_pk_bf16_f32 v51, v58, v59
	v_mul_f32_e32 v57, v53, v53
	v_mul_f32_e32 v59, v55, v55
	v_mul_f32_e32 v61, v105, v105
	v_fmac_f32_e32 v106, v60, v60
	v_fmac_f32_e32 v107, v62, v62
	v_fmac_f32_e32 v57, v52, v52
	v_fmac_f32_e32 v59, v54, v54
	v_mul_f32_e32 v63, v103, v103
	v_fmac_f32_e32 v108, v56, v56
	v_fmac_f32_e32 v61, v104, v104
	v_add_f32_e32 v56, v106, v107
	v_add_f32_e32 v57, v57, v59
	v_fmac_f32_e32 v109, v58, v58
	v_fmac_f32_e32 v63, v102, v102
	v_add_f32_e32 v56, v108, v56
	v_add_f32_e32 v57, v61, v57
	v_add_f32_e32 v56, v109, v56
	v_add_f32_e32 v57, v63, v57
	v_add_f32_e32 v58, v56, v57
	ds_bpermute_b32 v59, v186, v58
	v_lshl_add_u64 v[56:57], s[12:13], 0, v[110:111]
	v_lshl_add_u64 v[56:57], v[168:169], 1, v[56:57]
	global_store_dwordx4 v[56:57], v[48:51], off
	s_waitcnt lgkmcnt(0)
	s_nop 0
	v_add_f32_e32 v48, v58, v59
	ds_bpermute_b32 v49, v187, v48
	v_cvt_pk_bf16_f32 v50, v52, v53
	v_cvt_pk_bf16_f32 v51, v54, v55
	v_cvt_pk_bf16_f32 v52, v104, v105
	v_cvt_pk_bf16_f32 v53, v102, v103
	global_store_dwordx4 v[56:57], v[50:53], off offset:256
	s_and_saveexec_b64 s[34:35], s[4:5]
	s_cbranch_execz .LBB0_929
	v_lshlrev_b64 v[50:51], 6, v[100:101]
	v_lshl_add_u64 v[50:51], s[14:15], 0, v[50:51]
	v_lshl_add_u64 v[50:51], s[30:31], 2, v[50:51]
	s_lshl_b32 s8, s46, 2
	v_lshl_add_u64 v[50:51], v[50:51], 0, s[8:9]
	s_waitcnt lgkmcnt(0)
	v_add_f32_e32 v48, v48, v49
	global_store_dword v[50:51], v48, off
.LBB0_929:
	s_or_b64 exec, exec, s[34:35]
	v_lshlrev_b32_e32 v48, 16, v84
	s_waitcnt lgkmcnt(0)
	v_and_b32_e32 v49, 0xffff0000, v84
	v_lshlrev_b32_e32 v50, 16, v85
	v_and_b32_e32 v51, 0xffff0000, v85
	v_lshlrev_b32_e32 v52, 16, v86
	v_and_b32_e32 v53, 0xffff0000, v86
	v_lshlrev_b32_e32 v54, 16, v87
	v_and_b32_e32 v55, 0xffff0000, v87
	v_pk_add_f32 v[46:47], v[46:47], v[50:51]
	v_pk_add_f32 v[44:45], v[44:45], v[48:49]
	v_pk_add_f32 v[48:49], v[42:43], v[54:55]
	v_pk_add_f32 v[42:43], v[40:41], v[52:53]
	v_mul_f32_e32 v40, v45, v45
	v_mul_f32_e32 v41, v47, v47
	v_fmac_f32_e32 v40, v44, v44
	v_fmac_f32_e32 v41, v46, v46
	v_add_f32_e32 v40, v40, v41
	v_mul_f32_e32 v41, v43, v43
	v_fmac_f32_e32 v41, v42, v42
	v_add_f32_e32 v40, v41, v40
	v_mul_f32_e32 v41, v49, v49
	v_fmac_f32_e32 v41, v48, v48
	v_add_f32_e32 v52, v41, v40
	v_cvt_pk_bf16_f32 v40, v44, v45
	v_cvt_pk_bf16_f32 v41, v46, v47
	v_lshlrev_b32_e32 v44, 16, v80
	v_and_b32_e32 v45, 0xffff0000, v80
	v_lshlrev_b32_e32 v46, 16, v81
	v_and_b32_e32 v47, 0xffff0000, v81
	v_cvt_pk_bf16_f32 v42, v42, v43
	v_cvt_pk_bf16_f32 v43, v48, v49
	v_lshlrev_b32_e32 v48, 16, v82
	v_and_b32_e32 v49, 0xffff0000, v82
	v_pk_add_f32 v[38:39], v[38:39], v[46:47]
	v_pk_add_f32 v[36:37], v[36:37], v[44:45]
	v_pk_add_f32 v[46:47], v[32:33], v[48:49]
	v_mul_f32_e32 v32, v37, v37
	v_mul_f32_e32 v33, v39, v39
	v_fmac_f32_e32 v32, v36, v36
	v_fmac_f32_e32 v33, v38, v38
	v_lshlrev_b32_e32 v50, 16, v83
	v_and_b32_e32 v51, 0xffff0000, v83
	v_add_f32_e32 v32, v32, v33
	v_mul_f32_e32 v33, v47, v47
	v_pk_add_f32 v[44:45], v[34:35], v[50:51]
	v_fmac_f32_e32 v33, v46, v46
	v_add_f32_e32 v32, v33, v32
	v_mul_f32_e32 v33, v45, v45
	v_fmac_f32_e32 v33, v44, v44
	v_add_f32_e32 v32, v33, v32
	v_add_f32_e32 v35, v52, v32
	ds_bpermute_b32 v50, v186, v35
	v_lshl_add_u64 v[32:33], s[12:13], 0, v[98:99]
	v_lshl_add_u64 v[48:49], v[168:169], 1, v[32:33]
	global_store_dwordx4 v[48:49], v[40:43], off
	v_cvt_pk_bf16_f32 v34, v36, v37
	s_waitcnt lgkmcnt(0)
	v_add_f32_e32 v32, v35, v50
	ds_bpermute_b32 v33, v187, v32
	v_cvt_pk_bf16_f32 v35, v38, v39
	v_cvt_pk_bf16_f32 v36, v46, v47
	v_cvt_pk_bf16_f32 v37, v44, v45
	global_store_dwordx4 v[48:49], v[34:37], off offset:256
	s_and_saveexec_b64 s[34:35], s[4:5]
	s_cbranch_execz .LBB0_931
	v_lshlrev_b64 v[34:35], 6, v[96:97]
	v_lshl_add_u64 v[34:35], s[14:15], 0, v[34:35]
	v_lshl_add_u64 v[34:35], s[30:31], 2, v[34:35]
	s_lshl_b32 s8, s46, 2
	v_lshl_add_u64 v[34:35], v[34:35], 0, s[8:9]
	s_waitcnt lgkmcnt(0)
	v_add_f32_e32 v32, v32, v33
	global_store_dword v[34:35], v32, off
; __device__ __forceinline__ unsigned cvt_pk_bf16(float lo, float hi) { unsigned r; asm volatile("v_cvt_pk_bf16_f32 %0, %1, %2" : "=v"(r) : "v"(lo), "v"(hi)); return r; }
;     __device__ __forceinline__ void operator()(const f32x4 (&acc)[2][2][4][2], const Unit& u, int wr, int wc, int fr, int fq) const {
;     ...
;             for (int m = 0; m < 4; ++m) {
;                 const int row = row0 + ai * HALF + m * 16; const size_t off = (size_t)row * 1024 + col0;
;                 float ss = 0.f;
; #pragma unroll
;                 for (int bj = 0; bj < 2; ++bj) {
;                     f32x4 b0, b1;
;                     if (BASE_BF16) { const u32x4 w = bw[m][bj];
;                         b0 = (f32x4){__builtin_bit_cast(float, w.x << 16), __builtin_bit_cast(float, w.x & 0xffff0000u), __builtin_bit_cast(float, w.y << 16), __builtin_bit_cast(float, w.y & 0xffff0000u)};
;                         b1 = (f32x4){__builtin_bit_cast(float, w.z << 16), __builtin_bit_cast(float, w.z & 0xffff0000u), __builtin_bit_cast(float, w.w << 16), __builtin_bit_cast(float, w.w & 0xffff0000u)}; }
;                     else { b0 = bf[m][bj][0]; b1 = bf[m][bj][1]; }
;                     const f32x4 v0 = acc[ai][bj][m][0] + b0, v1 = acc[ai][bj][m][1] + b1;
;                     ss += (v0[0] * v0[0] + v0[1] * v0[1]) + (v0[2] * v0[2] + v0[3] * v0[3]) + (v1[0] * v1[0] + v1[1] * v1[1]) + (v1[2] * v1[2] + v1[3] * v1[3]);
;                     if (OUT_BF16) { u32x4 w; w.x = cvt_pk_bf16(v0[0], v0[1]); w.y = cvt_pk_bf16(v0[2], v0[3]); w.z = cvt_pk_bf16(v1[0], v1[1]); w.w = cvt_pk_bf16(v1[2], v1[3]);
;                         *(u32x4*)((bf16_t*)out + off + bj * HALF) = w; }
;                     else { *(f32x4*)((float*)out + off + bj * HALF) = v0; *(f32x4*)((float*)out + off + bj * HALF + 4) = v1; }
;                 }
;                 ss += __shfl_xor(ss, 16); ss += __shfl_xor(ss, 32);
;                 if (fq == 0) sspart[(size_t)row * 16 + u.pn * 4 + wc] = ss;
.LBB0_931:
	s_or_b64 exec, exec, s[34:35]
	v_lshlrev_b32_e32 v32, 16, v76
	s_waitcnt lgkmcnt(0)
	v_and_b32_e32 v33, 0xffff0000, v76
	v_lshlrev_b32_e32 v34, 16, v77
	v_and_b32_e32 v35, 0xffff0000, v77
	v_lshlrev_b32_e32 v36, 16, v78
	v_and_b32_e32 v37, 0xffff0000, v78
	v_lshlrev_b32_e32 v38, 16, v79
	v_and_b32_e32 v39, 0xffff0000, v79
	v_pk_add_f32 v[30:31], v[30:31], v[34:35]
	v_pk_add_f32 v[28:29], v[28:29], v[32:33]
	v_pk_add_f32 v[32:33], v[26:27], v[38:39]
	v_pk_add_f32 v[26:27], v[24:25], v[36:37]
	v_mul_f32_e32 v24, v29, v29
	v_mul_f32_e32 v25, v31, v31
	v_fmac_f32_e32 v24, v28, v28
	v_fmac_f32_e32 v25, v30, v30
	v_add_f32_e32 v24, v24, v25
	v_mul_f32_e32 v25, v27, v27
	v_fmac_f32_e32 v25, v26, v26
	v_add_f32_e32 v24, v25, v24
	v_mul_f32_e32 v25, v33, v33
	v_fmac_f32_e32 v25, v32, v32
	v_add_f32_e32 v36, v25, v24
	v_cvt_pk_bf16_f32 v24, v28, v29
	v_cvt_pk_bf16_f32 v25, v30, v31
	v_lshlrev_b32_e32 v28, 16, v72
	v_and_b32_e32 v29, 0xffff0000, v72
	v_lshlrev_b32_e32 v30, 16, v73
	v_and_b32_e32 v31, 0xffff0000, v73
	v_cvt_pk_bf16_f32 v26, v26, v27
	v_cvt_pk_bf16_f32 v27, v32, v33
	v_lshlrev_b32_e32 v32, 16, v74
	v_and_b32_e32 v33, 0xffff0000, v74
	v_pk_add_f32 v[22:23], v[22:23], v[30:31]
	v_pk_add_f32 v[20:21], v[20:21], v[28:29]
	v_pk_add_f32 v[30:31], v[16:17], v[32:33]
	v_mul_f32_e32 v16, v21, v21
	v_mul_f32_e32 v17, v23, v23
	v_fmac_f32_e32 v16, v20, v20
	v_fmac_f32_e32 v17, v22, v22
	v_lshlrev_b32_e32 v34, 16, v75
	v_and_b32_e32 v35, 0xffff0000, v75
	v_add_f32_e32 v16, v16, v17
	v_mul_f32_e32 v17, v31, v31
	v_pk_add_f32 v[28:29], v[18:19], v[34:35]
	v_fmac_f32_e32 v17, v30, v30
	v_add_f32_e32 v16, v17, v16
	v_mul_f32_e32 v17, v29, v29
	v_fmac_f32_e32 v17, v28, v28
	v_add_f32_e32 v16, v17, v16
	v_add_f32_e32 v19, v36, v16
	ds_bpermute_b32 v34, v186, v19
	v_lshl_add_u64 v[16:17], s[12:13], 0, v[94:95]
	v_lshl_add_u64 v[32:33], v[168:169], 1, v[16:17]
	global_store_dwordx4 v[32:33], v[24:27], off
	v_cvt_pk_bf16_f32 v18, v20, v21
	s_waitcnt lgkmcnt(0)
	v_add_f32_e32 v16, v19, v34
	ds_bpermute_b32 v17, v187, v16
	v_cvt_pk_bf16_f32 v19, v22, v23
	v_cvt_pk_bf16_f32 v20, v30, v31
	v_cvt_pk_bf16_f32 v21, v28, v29
	global_store_dwordx4 v[32:33], v[18:21], off offset:256
	s_and_saveexec_b64 s[34:35], s[4:5]
	s_cbranch_execz .LBB0_933
	v_lshlrev_b64 v[18:19], 6, v[92:93]
	v_lshl_add_u64 v[18:19], s[14:15], 0, v[18:19]
	v_lshl_add_u64 v[18:19], s[30:31], 2, v[18:19]
	s_lshl_b32 s8, s46, 2
	v_lshl_add_u64 v[18:19], v[18:19], 0, s[8:9]
	s_waitcnt lgkmcnt(0)
	v_add_f32_e32 v16, v16, v17
	global_store_dword v[18:19], v16, off
.LBB0_933:
	s_or_b64 exec, exec, s[34:35]
	v_lshlrev_b32_e32 v16, 16, v68
	s_waitcnt lgkmcnt(0)
	v_and_b32_e32 v17, 0xffff0000, v68
	v_lshlrev_b32_e32 v18, 16, v69
	v_and_b32_e32 v19, 0xffff0000, v69
	v_lshlrev_b32_e32 v20, 16, v70
	v_and_b32_e32 v21, 0xffff0000, v70
	v_lshlrev_b32_e32 v22, 16, v71
	v_and_b32_e32 v23, 0xffff0000, v71
	v_pk_add_f32 v[14:15], v[14:15], v[18:19]
	v_pk_add_f32 v[12:13], v[12:13], v[16:17]
	v_pk_add_f32 v[16:17], v[10:11], v[22:23]
	v_pk_add_f32 v[10:11], v[8:9], v[20:21]
	v_mul_f32_e32 v8, v13, v13
	v_mul_f32_e32 v9, v15, v15
	v_fmac_f32_e32 v8, v12, v12
	v_fmac_f32_e32 v9, v14, v14
	v_add_f32_e32 v8, v8, v9
	v_mul_f32_e32 v9, v11, v11
	v_fmac_f32_e32 v9, v10, v10
	v_add_f32_e32 v8, v9, v8
	v_mul_f32_e32 v9, v17, v17
	v_fmac_f32_e32 v9, v16, v16
	v_add_f32_e32 v20, v9, v8
	v_cvt_pk_bf16_f32 v8, v12, v13
	v_cvt_pk_bf16_f32 v9, v14, v15
	v_lshlrev_b32_e32 v12, 16, v64
	v_and_b32_e32 v13, 0xffff0000, v64
	v_lshlrev_b32_e32 v14, 16, v65
	v_and_b32_e32 v15, 0xffff0000, v65
	v_cvt_pk_bf16_f32 v10, v10, v11
	v_cvt_pk_bf16_f32 v11, v16, v17
	v_lshlrev_b32_e32 v16, 16, v66
	v_and_b32_e32 v17, 0xffff0000, v66
	v_pk_add_f32 v[6:7], v[6:7], v[14:15]
	v_pk_add_f32 v[4:5], v[4:5], v[12:13]
	v_pk_add_f32 v[14:15], v[0:1], v[16:17]
	v_mul_f32_e32 v0, v5, v5
	v_mul_f32_e32 v1, v7, v7
	v_fmac_f32_e32 v0, v4, v4
	v_fmac_f32_e32 v1, v6, v6
	v_lshlrev_b32_e32 v18, 16, v67
	v_and_b32_e32 v19, 0xffff0000, v67
	v_add_f32_e32 v0, v0, v1
	v_mul_f32_e32 v1, v15, v15
	v_pk_add_f32 v[12:13], v[2:3], v[18:19]
	v_fmac_f32_e32 v1, v14, v14
	v_add_f32_e32 v0, v1, v0
	v_mul_f32_e32 v1, v13, v13
	v_fmac_f32_e32 v1, v12, v12
	v_add_f32_e32 v0, v1, v0
	v_add_f32_e32 v3, v20, v0
	ds_bpermute_b32 v18, v186, v3
	v_lshl_add_u64 v[0:1], s[12:13], 0, v[90:91]
	v_lshl_add_u64 v[16:17], v[168:169], 1, v[0:1]
	global_store_dwordx4 v[16:17], v[8:11], off
	v_cvt_pk_bf16_f32 v2, v4, v5
	s_waitcnt lgkmcnt(0)
	v_add_f32_e32 v0, v3, v18
	ds_bpermute_b32 v1, v187, v0
	v_cvt_pk_bf16_f32 v3, v6, v7
	v_cvt_pk_bf16_f32 v4, v14, v15
	v_cvt_pk_bf16_f32 v5, v12, v13
	global_store_dwordx4 v[16:17], v[2:5], off offset:256
	s_and_saveexec_b64 s[34:35], s[4:5]
	s_cbranch_execz .LBB0_935
	v_lshlrev_b64 v[2:3], 6, v[88:89]
	v_lshl_add_u64 v[2:3], s[14:15], 0, v[2:3]
	v_lshl_add_u64 v[2:3], s[30:31], 2, v[2:3]
	s_lshl_b32 s8, s46, 2
	v_lshl_add_u64 v[2:3], v[2:3], 0, s[8:9]
	s_waitcnt lgkmcnt(0)
	v_add_f32_e32 v0, v0, v1
	global_store_dword v[2:3], v0, off

;     __device__ __forceinline__ void operator()(const f32x4 (&acc)[2][2][4][2], const Unit& u, int wr, int wc, int fr, int fq) const {
;     ...
;         for (int ai = 0; ai < 2; ++ai) {
;             u32x4 bw[4][2]; f32x4 bf[4][2][2];
; #pragma unroll
;             for (int m = 0; m < 4; ++m)
; #pragma unroll
;                 for (int bj = 0; bj < 2; ++bj) { const size_t off = (size_t)(row0 + ai * HALF + m * 16) * 1024 + col0 + bj * HALF;
;                     if (BASE_BF16) bw[m][bj] = *(const u32x4*)((const bf16_t*)base + off);
;                     else { bf[m][bj][0] = *(const f32x4*)((const float*)base + off); bf[m][bj][1] = *(const f32x4*)((const float*)base + off + 4); } }
; #pragma unroll
;             for (int m = 0; m < 4; ++m) {
;                 const int row = row0 + ai * HALF + m * 16; const size_t off = (size_t)row * 1024 + col0;
;                 float ss = 0.f;
; #pragma unroll
;                 for (int bj = 0; bj < 2; ++bj) {
;                     f32x4 b0, b1;
;                     if (BASE_BF16) { const u32x4 w = bw[m][bj];
;                         b0 = (f32x4){__builtin_bit_cast(float, w.x << 16), __builtin_bit_cast(float, w.x & 0xffff0000u), __builtin_bit_cast(float, w.y << 16), __builtin_bit_cast(float, w.y & 0xffff0000u)};
;                         b1 = (f32x4){__builtin_bit_cast(float, w.z << 16), __builtin_bit_cast(float, w.z & 0xffff0000u), __builtin_bit_cast(float, w.w << 16), __builtin_bit_cast(float, w.w & 0xffff0000u)}; }
;                     else { b0 = bf[m][bj][0]; b1 = bf[m][bj][1]; }
;                     const f32x4 v0 = acc[ai][bj][m][0] + b0, v1 = acc[ai][bj][m][1] + b1;
;                     ss += (v0[0] * v0[0] + v0[1] * v0[1]) + (v0[2] * v0[2] + v0[3] * v0[3]) + (v1[0] * v1[0] + v1[1] * v1[1]) + (v1[2] * v1[2] + v1[3] * v1[3]);
;                     if (OUT_BF16) { u32x4 w; w.x = cvt_pk_bf16(v0[0], v0[1]); w.y = cvt_pk_bf16(v0[2], v0[3]); w.z = cvt_pk_bf16(v1[0], v1[1]); w.w = cvt_pk_bf16(v1[2], v1[3]);
;                         *(u32x4*)((bf16_t*)out + off + bj * HALF) = w; }
;                     else { *(f32x4*)((float*)out + off + bj * HALF) = v0; *(f32x4*)((float*)out + off + bj * HALF + 4) = v1; }
;                 }
;                 ss += __shfl_xor(ss, 16); ss += __shfl_xor(ss, 32);
;                 if (fq == 0) sspart[(size_t)row * 16 + u.pn * 4 + wc] = ss;
.LBB0_1218:
	v_lshl_or_b32 v168, s8, 8, v190
	v_lshl_add_u32 v172, s34, 8, v188
	v_ashrrev_i32_e32 v169, 31, v168
	v_lshlrev_b64 v[202:203], 1, v[168:169]
	v_ashrrev_i32_e32 v173, 31, v172
	v_lshl_add_u64 v[170:171], s[12:13], 0, v[202:203]
	v_lshlrev_b64 v[204:205], 11, v[172:173]
	v_lshl_add_u64 v[128:129], v[170:171], 0, v[204:205]
	global_load_dwordx4 v[194:197], v[128:129], off
	global_load_dwordx4 v[198:201], v[128:129], off offset:256
	v_or_b32_e32 v182, 16, v172
	v_or_b32_e32 v178, 32, v172
	v_or_b32_e32 v174, 48, v172
	v_ashrrev_i32_e32 v183, 31, v182
	v_ashrrev_i32_e32 v179, 31, v178
	v_ashrrev_i32_e32 v175, 31, v174
	v_lshlrev_b64 v[184:185], 11, v[182:183]
	v_lshlrev_b64 v[180:181], 11, v[178:179]
	v_lshlrev_b64 v[176:177], 11, v[174:175]
	v_lshl_add_u64 v[128:129], v[170:171], 0, v[184:185]
	v_lshl_add_u64 v[130:131], v[170:171], 0, v[180:181]
	v_lshl_add_u64 v[206:207], v[170:171], 0, v[176:177]
	global_load_dwordx4 v[148:151], v[128:129], off
	global_load_dwordx4 v[144:147], v[128:129], off offset:256
	global_load_dwordx4 v[140:143], v[130:131], off
	global_load_dwordx4 v[136:139], v[130:131], off offset:256
	global_load_dwordx4 v[132:135], v[206:207], off
	s_nop 0
	global_load_dwordx4 v[128:131], v[206:207], off offset:256
	v_add_u32_e32 v248, 0x80, v172
	v_ashrrev_i32_e32 v249, 31, v248
	v_lshlrev_b64 v[248:249], 11, v[248:249]
	v_lshl_add_u64 v[248:249], v[170:171], 0, v[248:249]
	global_load_dwordx4 v[216:219], v[248:249], off
	global_load_dwordx4 v[220:223], v[248:249], off offset:256
	v_add_u32_e32 v248, 0x90, v172
	v_ashrrev_i32_e32 v249, 31, v248
	v_lshlrev_b64 v[248:249], 11, v[248:249]
	v_lshl_add_u64 v[248:249], v[170:171], 0, v[248:249]
	global_load_dwordx4 v[224:227], v[248:249], off
	global_load_dwordx4 v[228:231], v[248:249], off offset:256
	v_add_u32_e32 v248, 0xa0, v172
	v_ashrrev_i32_e32 v249, 31, v248
	v_lshlrev_b64 v[248:249], 11, v[248:249]
	v_lshl_add_u64 v[248:249], v[170:171], 0, v[248:249]
	global_load_dwordx4 v[232:235], v[248:249], off
	global_load_dwordx4 v[236:239], v[248:249], off offset:256
	v_add_u32_e32 v248, 0xb0, v172
	v_ashrrev_i32_e32 v249, 31, v248
	v_lshlrev_b64 v[248:249], 11, v[248:249]
	v_lshl_add_u64 v[248:249], v[170:171], 0, v[248:249]
	global_load_dwordx4 v[240:243], v[248:249], off
	global_load_dwordx4 v[244:247], v[248:249], off offset:256
	s_lshl_b32 s34, s8, 2
	s_ashr_i32 s35, s34, 31
	s_waitcnt vmcnt(8)
	v_lshlrev_b32_e32 v206, 16, v194
	v_and_b32_e32 v207, 0xffff0000, v194
	v_lshlrev_b32_e32 v194, 16, v195
	v_and_b32_e32 v195, 0xffff0000, v195
	v_lshlrev_b32_e32 v208, 16, v196
	v_and_b32_e32 v209, 0xffff0000, v196
	v_lshlrev_b32_e32 v196, 16, v197
	v_and_b32_e32 v197, 0xffff0000, v197
	v_lshlrev_b32_e32 v210, 16, v198
	v_and_b32_e32 v211, 0xffff0000, v198
	v_lshlrev_b32_e32 v198, 16, v199
	v_and_b32_e32 v199, 0xffff0000, v199
	v_lshlrev_b32_e32 v214, 16, v200
	v_and_b32_e32 v215, 0xffff0000, v200
	v_lshlrev_b32_e32 v200, 16, v201
	v_and_b32_e32 v201, 0xffff0000, v201
	v_pk_add_f32 v[126:127], v[126:127], v[194:195]
	v_pk_add_f32 v[124:125], v[124:125], v[206:207]
	v_pk_add_f32 v[122:123], v[122:123], v[196:197]
	v_pk_add_f32 v[120:121], v[120:121], v[208:209]
	v_pk_add_f32 v[118:119], v[118:119], v[198:199]
	v_pk_add_f32 v[116:117], v[116:117], v[210:211]
	v_pk_add_f32 v[194:195], v[114:115], v[200:201]
	v_pk_add_f32 v[196:197], v[112:113], v[214:215]
	v_mul_f32_e32 v198, v125, v125
	v_mul_f32_e32 v199, v127, v127
	v_mul_f32_e32 v200, v121, v121
	v_mul_f32_e32 v201, v123, v123
	v_cvt_pk_bf16_f32 v112, v124, v125
	v_cvt_pk_bf16_f32 v113, v126, v127
	v_cvt_pk_bf16_f32 v114, v120, v121
	v_cvt_pk_bf16_f32 v115, v122, v123
	v_mul_f32_e32 v121, v117, v117
	v_mul_f32_e32 v123, v119, v119
	v_mul_f32_e32 v125, v197, v197
	v_fmac_f32_e32 v198, v124, v124
	v_fmac_f32_e32 v199, v126, v126
	v_fmac_f32_e32 v121, v116, v116
	v_fmac_f32_e32 v123, v118, v118
	v_mul_f32_e32 v127, v195, v195
	v_fmac_f32_e32 v200, v120, v120
	v_fmac_f32_e32 v125, v196, v196
	v_add_f32_e32 v120, v198, v199
	v_add_f32_e32 v121, v121, v123
	v_fmac_f32_e32 v201, v122, v122
	v_fmac_f32_e32 v127, v194, v194
	v_add_f32_e32 v120, v200, v120
	v_add_f32_e32 v121, v125, v121
	v_add_f32_e32 v120, v201, v120
	v_add_f32_e32 v121, v127, v121
	v_add_f32_e32 v122, v120, v121
	ds_bpermute_b32 v123, v186, v122
	v_lshl_add_u64 v[120:121], s[14:15], 0, v[204:205]
	v_lshl_add_u64 v[120:121], v[120:121], 0, v[202:203]
	global_store_dwordx4 v[120:121], v[112:115], off
	s_waitcnt lgkmcnt(0)
	s_nop 0
	v_add_f32_e32 v112, v122, v123
	ds_bpermute_b32 v113, v187, v112
	v_cvt_pk_bf16_f32 v114, v116, v117
	v_cvt_pk_bf16_f32 v115, v118, v119
	v_cvt_pk_bf16_f32 v116, v196, v197
	v_cvt_pk_bf16_f32 v117, v194, v195
	global_store_dwordx4 v[120:121], v[114:117], off offset:256
	s_and_saveexec_b64 s[36:37], s[4:5]
	s_cbranch_execz .LBB0_1220
	v_lshlrev_b64 v[114:115], 6, v[172:173]
	v_lshl_add_u64 v[114:115], s[16:17], 0, v[114:115]
	v_lshl_add_u64 v[114:115], s[34:35], 2, v[114:115]
	s_lshl_b32 s8, s48, 2
	v_lshl_add_u64 v[114:115], v[114:115], 0, s[8:9]
	s_waitcnt lgkmcnt(0)
	v_add_f32_e32 v112, v112, v113
	global_store_dword v[114:115], v112, off

;     __device__ __forceinline__ void operator()(const f32x4 (&acc)[2][2][4][2], const Unit& u, int wr, int wc, int fr, int fq) const {
;     ...
;         for (int ai = 0; ai < 2; ++ai) {
;             u32x4 bw[4][2]; f32x4 bf[4][2][2];
; #pragma unroll
;             for (int m = 0; m < 4; ++m)
; #pragma unroll
;                 for (int bj = 0; bj < 2; ++bj) { const size_t off = (size_t)(row0 + ai * HALF + m * 16) * 1024 + col0 + bj * HALF;
;                     if (BASE_BF16) bw[m][bj] = *(const u32x4*)((const bf16_t*)base + off);
;                     else { bf[m][bj][0] = *(const f32x4*)((const float*)base + off); bf[m][bj][1] = *(const f32x4*)((const float*)base + off + 4); } }
; #pragma unroll
;             for (int m = 0; m < 4; ++m) {
;                 const int row = row0 + ai * HALF + m * 16; const size_t off = (size_t)row * 1024 + col0;
;                 float ss = 0.f;
; #pragma unroll
;                 for (int bj = 0; bj < 2; ++bj) {
;                     f32x4 b0, b1;
;                     if (BASE_BF16) { const u32x4 w = bw[m][bj];
;                         b0 = (f32x4){__builtin_bit_cast(float, w.x << 16), __builtin_bit_cast(float, w.x & 0xffff0000u), __builtin_bit_cast(float, w.y << 16), __builtin_bit_cast(float, w.y & 0xffff0000u)};
;                         b1 = (f32x4){__builtin_bit_cast(float, w.z << 16), __builtin_bit_cast(float, w.z & 0xffff0000u), __builtin_bit_cast(float, w.w << 16), __builtin_bit_cast(float, w.w & 0xffff0000u)}; }
;                     else { b0 = bf[m][bj][0]; b1 = bf[m][bj][1]; }
;                     const f32x4 v0 = acc[ai][bj][m][0] + b0, v1 = acc[ai][bj][m][1] + b1;
;                     ss += (v0[0] * v0[0] + v0[1] * v0[1]) + (v0[2] * v0[2] + v0[3] * v0[3]) + (v1[0] * v1[0] + v1[1] * v1[1]) + (v1[2] * v1[2] + v1[3] * v1[3]);
;                     if (OUT_BF16) { u32x4 w; w.x = cvt_pk_bf16(v0[0], v0[1]); w.y = cvt_pk_bf16(v0[2], v0[3]); w.z = cvt_pk_bf16(v1[0], v1[1]); w.w = cvt_pk_bf16(v1[2], v1[3]);
;                         *(u32x4*)((bf16_t*)out + off + bj * HALF) = w; }
;                     else { *(f32x4*)((float*)out + off + bj * HALF) = v0; *(f32x4*)((float*)out + off + bj * HALF + 4) = v1; }
;                 }
;                 ss += __shfl_xor(ss, 16); ss += __shfl_xor(ss, 32);
;                 if (fq == 0) sspart[(size_t)row * 16 + u.pn * 4 + wc] = ss;
.LBB0_1226:
	s_or_b64 exec, exec, s[36:37]
	v_add_u32_e32 v100, 0x80, v172
	v_ashrrev_i32_e32 v101, 31, v100
	v_lshlrev_b64 v[110:111], 11, v[100:101]
	s_waitcnt lgkmcnt(0)
	v_lshl_add_u64 v[64:65], v[170:171], 0, v[110:111]
	v_add_u32_e32 v96, 0x90, v172
	v_add_u32_e32 v92, 0xa0, v172
	v_add_u32_e32 v88, 0xb0, v172
	v_ashrrev_i32_e32 v97, 31, v96
	v_ashrrev_i32_e32 v93, 31, v92
	v_ashrrev_i32_e32 v89, 31, v88
	v_lshlrev_b64 v[98:99], 11, v[96:97]
	v_lshlrev_b64 v[94:95], 11, v[92:93]
	v_lshlrev_b64 v[90:91], 11, v[88:89]
	v_lshl_add_u64 v[64:65], v[170:171], 0, v[98:99]
	v_lshl_add_u64 v[66:67], v[170:171], 0, v[94:95]
	v_lshl_add_u64 v[112:113], v[170:171], 0, v[90:91]
	s_nop 0
	s_waitcnt vmcnt(8)
	v_mov_b32_e32 v102, v216
	v_mov_b32_e32 v103, v217
	v_mov_b32_e32 v104, v218
	v_mov_b32_e32 v105, v219
	v_mov_b32_e32 v106, v220
	v_mov_b32_e32 v107, v221
	v_mov_b32_e32 v108, v222
	v_mov_b32_e32 v109, v223
	v_mov_b32_e32 v84, v224
	v_mov_b32_e32 v85, v225
	v_mov_b32_e32 v86, v226
	v_mov_b32_e32 v87, v227
	v_mov_b32_e32 v80, v228
	v_mov_b32_e32 v81, v229
	v_mov_b32_e32 v82, v230
	v_mov_b32_e32 v83, v231
	v_mov_b32_e32 v76, v232
	v_mov_b32_e32 v77, v233
	v_mov_b32_e32 v78, v234
	v_mov_b32_e32 v79, v235
	v_mov_b32_e32 v72, v236
	v_mov_b32_e32 v73, v237
	v_mov_b32_e32 v74, v238
	v_mov_b32_e32 v75, v239
	v_mov_b32_e32 v68, v240
	v_mov_b32_e32 v69, v241
	v_mov_b32_e32 v70, v242
	v_mov_b32_e32 v71, v243
	v_mov_b32_e32 v64, v244
	v_mov_b32_e32 v65, v245
	v_mov_b32_e32 v66, v246
	v_mov_b32_e32 v67, v247
	v_lshlrev_b32_e32 v112, 16, v102
	v_and_b32_e32 v113, 0xffff0000, v102
	v_lshlrev_b32_e32 v102, 16, v103
	v_and_b32_e32 v103, 0xffff0000, v103
	v_lshlrev_b32_e32 v114, 16, v104
	v_and_b32_e32 v115, 0xffff0000, v104
	v_lshlrev_b32_e32 v104, 16, v105
	v_and_b32_e32 v105, 0xffff0000, v105
	v_lshlrev_b32_e32 v116, 16, v106
	v_and_b32_e32 v117, 0xffff0000, v106
	v_lshlrev_b32_e32 v106, 16, v107
	v_and_b32_e32 v107, 0xffff0000, v107
	v_lshlrev_b32_e32 v118, 16, v108
	v_and_b32_e32 v119, 0xffff0000, v108
	v_lshlrev_b32_e32 v108, 16, v109
	v_and_b32_e32 v109, 0xffff0000, v109
	v_pk_add_f32 v[62:63], v[62:63], v[102:103]
	v_pk_add_f32 v[60:61], v[60:61], v[112:113]
	v_pk_add_f32 v[58:59], v[58:59], v[104:105]
	v_pk_add_f32 v[56:57], v[56:57], v[114:115]
	v_pk_add_f32 v[54:55], v[54:55], v[106:107]
	v_pk_add_f32 v[52:53], v[52:53], v[116:117]
	v_pk_add_f32 v[102:103], v[50:51], v[108:109]
	v_pk_add_f32 v[104:105], v[48:49], v[118:119]
	v_mul_f32_e32 v106, v61, v61
	v_mul_f32_e32 v107, v63, v63
	v_mul_f32_e32 v108, v57, v57
	v_mul_f32_e32 v109, v59, v59
	v_cvt_pk_bf16_f32 v48, v60, v61
	v_cvt_pk_bf16_f32 v49, v62, v63
	v_cvt_pk_bf16_f32 v50, v56, v57
	v_cvt_pk_bf16_f32 v51, v58, v59
	v_mul_f32_e32 v57, v53, v53
	v_mul_f32_e32 v59, v55, v55
	v_mul_f32_e32 v61, v105, v105
	v_fmac_f32_e32 v106, v60, v60
	v_fmac_f32_e32 v107, v62, v62
	v_fmac_f32_e32 v57, v52, v52
	v_fmac_f32_e32 v59, v54, v54
	v_mul_f32_e32 v63, v103, v103
	v_fmac_f32_e32 v108, v56, v56
	v_fmac_f32_e32 v61, v104, v104
	v_add_f32_e32 v56, v106, v107
	v_add_f32_e32 v57, v57, v59
	v_fmac_f32_e32 v109, v58, v58
	v_fmac_f32_e32 v63, v102, v102
	v_add_f32_e32 v56, v108, v56
	v_add_f32_e32 v57, v61, v57
	v_add_f32_e32 v56, v109, v56
	v_add_f32_e32 v57, v63, v57
	v_add_f32_e32 v58, v56, v57
	ds_bpermute_b32 v59, v186, v58
	v_lshl_add_u64 v[56:57], s[14:15], 0, v[110:111]
	v_lshl_add_u64 v[56:57], v[168:169], 1, v[56:57]
	global_store_dwordx4 v[56:57], v[48:51], off
	s_waitcnt lgkmcnt(0)
	s_nop 0
	v_add_f32_e32 v48, v58, v59
	ds_bpermute_b32 v49, v187, v48
	v_cvt_pk_bf16_f32 v50, v52, v53
	v_cvt_pk_bf16_f32 v51, v54, v55
	v_cvt_pk_bf16_f32 v52, v104, v105
	v_cvt_pk_bf16_f32 v53, v102, v103
	global_store_dwordx4 v[56:57], v[50:53], off offset:256
	s_and_saveexec_b64 s[36:37], s[4:5]
	s_cbranch_execz .LBB0_1228
	v_lshlrev_b64 v[50:51], 6, v[100:101]
	v_lshl_add_u64 v[50:51], s[16:17], 0, v[50:51]
	v_lshl_add_u64 v[50:51], s[34:35], 2, v[50:51]
	s_lshl_b32 s8, s48, 2
	v_lshl_add_u64 v[50:51], v[50:51], 0, s[8:9]
	s_waitcnt lgkmcnt(0)
	v_add_f32_e32 v48, v48, v49
	global_store_dword v[50:51], v48, off
.LBB0_1228:
	s_or_b64 exec, exec, s[36:37]
	v_lshlrev_b32_e32 v48, 16, v84
	s_waitcnt lgkmcnt(0)
	v_and_b32_e32 v49, 0xffff0000, v84
	v_lshlrev_b32_e32 v50, 16, v85
	v_and_b32_e32 v51, 0xffff0000, v85
	v_lshlrev_b32_e32 v52, 16, v86
	v_and_b32_e32 v53, 0xffff0000, v86
	v_lshlrev_b32_e32 v54, 16, v87
	v_and_b32_e32 v55, 0xffff0000, v87
	v_pk_add_f32 v[46:47], v[46:47], v[50:51]
	v_pk_add_f32 v[44:45], v[44:45], v[48:49]
	v_pk_add_f32 v[48:49], v[42:43], v[54:55]
	v_pk_add_f32 v[42:43], v[40:41], v[52:53]
	v_mul_f32_e32 v40, v45, v45
	v_mul_f32_e32 v41, v47, v47
	v_fmac_f32_e32 v40, v44, v44
	v_fmac_f32_e32 v41, v46, v46
	v_add_f32_e32 v40, v40, v41
	v_mul_f32_e32 v41, v43, v43
	v_fmac_f32_e32 v41, v42, v42
	v_add_f32_e32 v40, v41, v40
	v_mul_f32_e32 v41, v49, v49
	v_fmac_f32_e32 v41, v48, v48
	v_add_f32_e32 v52, v41, v40
	v_cvt_pk_bf16_f32 v40, v44, v45
	v_cvt_pk_bf16_f32 v41, v46, v47
	v_lshlrev_b32_e32 v44, 16, v80
	v_and_b32_e32 v45, 0xffff0000, v80
	v_lshlrev_b32_e32 v46, 16, v81
	v_and_b32_e32 v47, 0xffff0000, v81
	v_cvt_pk_bf16_f32 v42, v42, v43
	v_cvt_pk_bf16_f32 v43, v48, v49
	v_lshlrev_b32_e32 v48, 16, v82
	v_and_b32_e32 v49, 0xffff0000, v82
	v_pk_add_f32 v[38:39], v[38:39], v[46:47]
	v_pk_add_f32 v[36:37], v[36:37], v[44:45]
	v_pk_add_f32 v[46:47], v[32:33], v[48:49]
	v_mul_f32_e32 v32, v37, v37
	v_mul_f32_e32 v33, v39, v39
	v_fmac_f32_e32 v32, v36, v36
	v_fmac_f32_e32 v33, v38, v38
	v_lshlrev_b32_e32 v50, 16, v83
	v_and_b32_e32 v51, 0xffff0000, v83
	v_add_f32_e32 v32, v32, v33
	v_mul_f32_e32 v33, v47, v47
	v_pk_add_f32 v[44:45], v[34:35], v[50:51]
	v_fmac_f32_e32 v33, v46, v46
	v_add_f32_e32 v32, v33, v32
	v_mul_f32_e32 v33, v45, v45
	v_fmac_f32_e32 v33, v44, v44
	v_add_f32_e32 v32, v33, v32
	v_add_f32_e32 v35, v52, v32
	ds_bpermute_b32 v50, v186, v35
	v_lshl_add_u64 v[32:33], s[14:15], 0, v[98:99]
	v_lshl_add_u64 v[48:49], v[168:169], 1, v[32:33]
	global_store_dwordx4 v[48:49], v[40:43], off
	v_cvt_pk_bf16_f32 v34, v36, v37
	s_waitcnt lgkmcnt(0)
	v_add_f32_e32 v32, v35, v50
	ds_bpermute_b32 v33, v187, v32
	v_cvt_pk_bf16_f32 v35, v38, v39
	v_cvt_pk_bf16_f32 v36, v46, v47
	v_cvt_pk_bf16_f32 v37, v44, v45
	global_store_dwordx4 v[48:49], v[34:37], off offset:256
	s_and_saveexec_b64 s[36:37], s[4:5]
	s_cbranch_execz .LBB0_1230
	v_lshlrev_b64 v[34:35], 6, v[96:97]
	v_lshl_add_u64 v[34:35], s[16:17], 0, v[34:35]
	v_lshl_add_u64 v[34:35], s[34:35], 2, v[34:35]
	s_lshl_b32 s8, s48, 2
	v_lshl_add_u64 v[34:35], v[34:35], 0, s[8:9]
	s_waitcnt lgkmcnt(0)
	v_add_f32_e32 v32, v32, v33
	global_store_dword v[34:35], v32, off
; __device__ __forceinline__ unsigned cvt_pk_bf16(float lo, float hi) { unsigned r; asm volatile("v_cvt_pk_bf16_f32 %0, %1, %2" : "=v"(r) : "v"(lo), "v"(hi)); return r; }
;     __device__ __forceinline__ void operator()(const f32x4 (&acc)[2][2][4][2], const Unit& u, int wr, int wc, int fr, int fq) const {
;     ...
;             for (int m = 0; m < 4; ++m) {
;                 const int row = row0 + ai * HALF + m * 16; const size_t off = (size_t)row * 1024 + col0;
;                 float ss = 0.f;
; #pragma unroll
;                 for (int bj = 0; bj < 2; ++bj) {
;                     f32x4 b0, b1;
;                     if (BASE_BF16) { const u32x4 w = bw[m][bj];
;                         b0 = (f32x4){__builtin_bit_cast(float, w.x << 16), __builtin_bit_cast(float, w.x & 0xffff0000u), __builtin_bit_cast(float, w.y << 16), __builtin_bit_cast(float, w.y & 0xffff0000u)};
;                         b1 = (f32x4){__builtin_bit_cast(float, w.z << 16), __builtin_bit_cast(float, w.z & 0xffff0000u), __builtin_bit_cast(float, w.w << 16), __builtin_bit_cast(float, w.w & 0xffff0000u)}; }
;                     else { b0 = bf[m][bj][0]; b1 = bf[m][bj][1]; }
;                     const f32x4 v0 = acc[ai][bj][m][0] + b0, v1 = acc[ai][bj][m][1] + b1;
;                     ss += (v0[0] * v0[0] + v0[1] * v0[1]) + (v0[2] * v0[2] + v0[3] * v0[3]) + (v1[0] * v1[0] + v1[1] * v1[1]) + (v1[2] * v1[2] + v1[3] * v1[3]);
;                     if (OUT_BF16) { u32x4 w; w.x = cvt_pk_bf16(v0[0], v0[1]); w.y = cvt_pk_bf16(v0[2], v0[3]); w.z = cvt_pk_bf16(v1[0], v1[1]); w.w = cvt_pk_bf16(v1[2], v1[3]);
;                         *(u32x4*)((bf16_t*)out + off + bj * HALF) = w; }
;                     else { *(f32x4*)((float*)out + off + bj * HALF) = v0; *(f32x4*)((float*)out + off + bj * HALF + 4) = v1; }
;                 }
;                 ss += __shfl_xor(ss, 16); ss += __shfl_xor(ss, 32);
;                 if (fq == 0) sspart[(size_t)row * 16 + u.pn * 4 + wc] = ss;
.LBB0_1230:
	s_or_b64 exec, exec, s[36:37]
	v_lshlrev_b32_e32 v32, 16, v76
	s_waitcnt lgkmcnt(0)
	v_and_b32_e32 v33, 0xffff0000, v76
	v_lshlrev_b32_e32 v34, 16, v77
	v_and_b32_e32 v35, 0xffff0000, v77
	v_lshlrev_b32_e32 v36, 16, v78
	v_and_b32_e32 v37, 0xffff0000, v78
	v_lshlrev_b32_e32 v38, 16, v79
	v_and_b32_e32 v39, 0xffff0000, v79
	v_pk_add_f32 v[30:31], v[30:31], v[34:35]
	v_pk_add_f32 v[28:29], v[28:29], v[32:33]
	v_pk_add_f32 v[32:33], v[26:27], v[38:39]
	v_pk_add_f32 v[26:27], v[24:25], v[36:37]
	v_mul_f32_e32 v24, v29, v29
	v_mul_f32_e32 v25, v31, v31
	v_fmac_f32_e32 v24, v28, v28
	v_fmac_f32_e32 v25, v30, v30
	v_add_f32_e32 v24, v24, v25
	v_mul_f32_e32 v25, v27, v27
	v_fmac_f32_e32 v25, v26, v26
	v_add_f32_e32 v24, v25, v24
	v_mul_f32_e32 v25, v33, v33
	v_fmac_f32_e32 v25, v32, v32
	v_add_f32_e32 v36, v25, v24
	v_cvt_pk_bf16_f32 v24, v28, v29
	v_cvt_pk_bf16_f32 v25, v30, v31
	v_lshlrev_b32_e32 v28, 16, v72
	v_and_b32_e32 v29, 0xffff0000, v72
	v_lshlrev_b32_e32 v30, 16, v73
	v_and_b32_e32 v31, 0xffff0000, v73
	v_cvt_pk_bf16_f32 v26, v26, v27
	v_cvt_pk_bf16_f32 v27, v32, v33
	v_lshlrev_b32_e32 v32, 16, v74
	v_and_b32_e32 v33, 0xffff0000, v74
	v_pk_add_f32 v[22:23], v[22:23], v[30:31]
	v_pk_add_f32 v[20:21], v[20:21], v[28:29]
	v_pk_add_f32 v[30:31], v[16:17], v[32:33]
	v_mul_f32_e32 v16, v21, v21
	v_mul_f32_e32 v17, v23, v23
	v_fmac_f32_e32 v16, v20, v20
	v_fmac_f32_e32 v17, v22, v22
	v_lshlrev_b32_e32 v34, 16, v75
	v_and_b32_e32 v35, 0xffff0000, v75
	v_add_f32_e32 v16, v16, v17
	v_mul_f32_e32 v17, v31, v31
	v_pk_add_f32 v[28:29], v[18:19], v[34:35]
	v_fmac_f32_e32 v17, v30, v30
	v_add_f32_e32 v16, v17, v16
	v_mul_f32_e32 v17, v29, v29
	v_fmac_f32_e32 v17, v28, v28
	v_add_f32_e32 v16, v17, v16
	v_add_f32_e32 v19, v36, v16
	ds_bpermute_b32 v34, v186, v19
	v_lshl_add_u64 v[16:17], s[14:15], 0, v[94:95]
	v_lshl_add_u64 v[32:33], v[168:169], 1, v[16:17]
	global_store_dwordx4 v[32:33], v[24:27], off
	v_cvt_pk_bf16_f32 v18, v20, v21
	s_waitcnt lgkmcnt(0)
	v_add_f32_e32 v16, v19, v34
	ds_bpermute_b32 v17, v187, v16
	v_cvt_pk_bf16_f32 v19, v22, v23
	v_cvt_pk_bf16_f32 v20, v30, v31
	v_cvt_pk_bf16_f32 v21, v28, v29
	global_store_dwordx4 v[32:33], v[18:21], off offset:256
	s_and_saveexec_b64 s[36:37], s[4:5]
	s_cbranch_execz .LBB0_1232
	v_lshlrev_b64 v[18:19], 6, v[92:93]
	v_lshl_add_u64 v[18:19], s[16:17], 0, v[18:19]
	v_lshl_add_u64 v[18:19], s[34:35], 2, v[18:19]
	s_lshl_b32 s8, s48, 2
	v_lshl_add_u64 v[18:19], v[18:19], 0, s[8:9]
	s_waitcnt lgkmcnt(0)
	v_add_f32_e32 v16, v16, v17
	global_store_dword v[18:19], v16, off
.LBB0_1232:
	s_or_b64 exec, exec, s[36:37]
	v_lshlrev_b32_e32 v16, 16, v68
	s_waitcnt lgkmcnt(0)
	v_and_b32_e32 v17, 0xffff0000, v68
	v_lshlrev_b32_e32 v18, 16, v69
	v_and_b32_e32 v19, 0xffff0000, v69
	v_lshlrev_b32_e32 v20, 16, v70
	v_and_b32_e32 v21, 0xffff0000, v70
	v_lshlrev_b32_e32 v22, 16, v71
	v_and_b32_e32 v23, 0xffff0000, v71
	v_pk_add_f32 v[14:15], v[14:15], v[18:19]
	v_pk_add_f32 v[12:13], v[12:13], v[16:17]
	v_pk_add_f32 v[16:17], v[10:11], v[22:23]
	v_pk_add_f32 v[10:11], v[8:9], v[20:21]
	v_mul_f32_e32 v8, v13, v13
	v_mul_f32_e32 v9, v15, v15
	v_fmac_f32_e32 v8, v12, v12
	v_fmac_f32_e32 v9, v14, v14
	v_add_f32_e32 v8, v8, v9
	v_mul_f32_e32 v9, v11, v11
	v_fmac_f32_e32 v9, v10, v10
	v_add_f32_e32 v8, v9, v8
	v_mul_f32_e32 v9, v17, v17
	v_fmac_f32_e32 v9, v16, v16
	v_add_f32_e32 v20, v9, v8
	v_cvt_pk_bf16_f32 v8, v12, v13
	v_cvt_pk_bf16_f32 v9, v14, v15
	v_lshlrev_b32_e32 v12, 16, v64
	v_and_b32_e32 v13, 0xffff0000, v64
	v_lshlrev_b32_e32 v14, 16, v65
	v_and_b32_e32 v15, 0xffff0000, v65
	v_cvt_pk_bf16_f32 v10, v10, v11
	v_cvt_pk_bf16_f32 v11, v16, v17
	v_lshlrev_b32_e32 v16, 16, v66
	v_and_b32_e32 v17, 0xffff0000, v66
	v_pk_add_f32 v[6:7], v[6:7], v[14:15]
	v_pk_add_f32 v[4:5], v[4:5], v[12:13]
	v_pk_add_f32 v[14:15], v[0:1], v[16:17]
	v_mul_f32_e32 v0, v5, v5
	v_mul_f32_e32 v1, v7, v7
	v_fmac_f32_e32 v0, v4, v4
	v_fmac_f32_e32 v1, v6, v6
	v_lshlrev_b32_e32 v18, 16, v67
	v_and_b32_e32 v19, 0xffff0000, v67
	v_add_f32_e32 v0, v0, v1
	v_mul_f32_e32 v1, v15, v15
	v_pk_add_f32 v[12:13], v[2:3], v[18:19]
	v_fmac_f32_e32 v1, v14, v14
	v_add_f32_e32 v0, v1, v0
	v_mul_f32_e32 v1, v13, v13
	v_fmac_f32_e32 v1, v12, v12
	v_add_f32_e32 v0, v1, v0
	v_add_f32_e32 v3, v20, v0
	ds_bpermute_b32 v18, v186, v3
	v_lshl_add_u64 v[0:1], s[14:15], 0, v[90:91]
	v_lshl_add_u64 v[16:17], v[168:169], 1, v[0:1]
	global_store_dwordx4 v[16:17], v[8:11], off
	v_cvt_pk_bf16_f32 v2, v4, v5
	s_waitcnt lgkmcnt(0)
	v_add_f32_e32 v0, v3, v18
	ds_bpermute_b32 v1, v187, v0
	v_cvt_pk_bf16_f32 v3, v6, v7
	v_cvt_pk_bf16_f32 v4, v14, v15
	v_cvt_pk_bf16_f32 v5, v12, v13
	global_store_dwordx4 v[16:17], v[2:5], off offset:256
	s_and_saveexec_b64 s[36:37], s[4:5]
	s_cbranch_execz .LBB0_1234
	v_lshlrev_b64 v[2:3], 6, v[88:89]
	v_lshl_add_u64 v[2:3], s[16:17], 0, v[2:3]
	v_lshl_add_u64 v[2:3], s[34:35], 2, v[2:3]
	s_lshl_b32 s8, s48, 2
	v_lshl_add_u64 v[2:3], v[2:3], 0, s[8:9]
	s_waitcnt lgkmcnt(0)
	v_add_f32_e32 v0, v0, v1
	global_store_dword v[2:3], v0, off
